# attention steady loop: 3 LDS-DMA issues per step moved from a bunch between QK and PV phases into separate PV gaps
# speedup vs baseline: 1.0422x; 1.0422x over previous
.LBB0_304:
	s_mov_b32 s37, s28
	s_mov_b32 s14, s27
	v_lshl_add_u32 v65, s15, 1, v239
	ds_read_b64_tr_b16 v[72:73], v65 offset:24576
	ds_read_b64_tr_b16 v[74:75], v65 offset:25088
	v_add_f32_e32 v68, v96, v97
	v_add_f32_e32 v68, v98, v68
	v_add_f32_e32 v68, v99, v68
	v_add_f32_e32 v68, v100, v68
	v_add_f32_e32 v68, v101, v68
	v_cvt_pk_bf16_f32 v172, v96, v97
	v_cvt_pk_bf16_f32 v173, v98, v99
	s_waitcnt lgkmcnt(9)
	v_mfma_f32_32x32x16_bf16 v[128:143], v[204:207], v[168:171], 0
	ds_read_b64_tr_b16 v[76:77], v65 offset:28672
	ds_read_b64_tr_b16 v[78:79], v65 offset:29184
	v_add_f32_e32 v68, v102, v68
	v_add_f32_e32 v68, v103, v68
	v_add_f32_e32 v68, v104, v68
	v_add_f32_e32 v68, v105, v68
	v_cvt_pk_bf16_f32 v174, v100, v101
	v_cvt_pk_bf16_f32 v175, v102, v103
	s_waitcnt lgkmcnt(10)
	v_mfma_f32_32x32x16_bf16 v[112:127], v[200:203], v[168:171], 0
	ds_read_b64_tr_b16 v[96:97], v65 offset:32768
	ds_read_b64_tr_b16 v[98:99], v65 offset:33280
	v_add_f32_e32 v68, v106, v68
	v_add_f32_e32 v68, v107, v68
	v_add_f32_e32 v68, v108, v68
	v_add_f32_e32 v68, v109, v68
	v_cvt_pk_bf16_f32 v164, v104, v105
	v_cvt_pk_bf16_f32 v165, v106, v107
	s_waitcnt lgkmcnt(11)
	v_mfma_f32_32x32x16_bf16 v[128:143], v[196:199], v[160:163], v[128:143]
	ds_read_b64_tr_b16 v[100:101], v65 offset:36864
	ds_read_b64_tr_b16 v[102:103], v65 offset:37376
	v_add_f32_e32 v68, v110, v68
	v_add_f32_e32 v68, v111, v68
	v_add_f32_e32 v68, v80, v68
	v_add_f32_e32 v68, v81, v68
	v_cvt_pk_bf16_f32 v166, v108, v109
	v_cvt_pk_bf16_f32 v167, v110, v111
	s_waitcnt lgkmcnt(12)
	v_mfma_f32_32x32x16_bf16 v[112:127], v[192:195], v[160:163], v[112:127]
	ds_read_b64_tr_b16 v[104:105], v65 offset:25600
	ds_read_b64_tr_b16 v[106:107], v65 offset:26112
	v_add_f32_e32 v68, v82, v68
	v_add_f32_e32 v68, v83, v68
	v_add_f32_e32 v68, v84, v68
	v_add_f32_e32 v68, v85, v68
	v_cvt_pk_bf16_f32 v156, v80, v81
	v_cvt_pk_bf16_f32 v157, v82, v83
	s_waitcnt lgkmcnt(13)
	v_mfma_f32_32x32x16_bf16 v[128:143], v[188:191], v[152:155], v[128:143]
	ds_read_b64_tr_b16 v[80:81], v65 offset:29696
	ds_read_b64_tr_b16 v[82:83], v65 offset:30208
	v_add_f32_e32 v68, v86, v68
	v_add_f32_e32 v68, v87, v68
	v_add_f32_e32 v68, v88, v68
	v_add_f32_e32 v68, v89, v68
	v_cvt_pk_bf16_f32 v158, v84, v85
	v_cvt_pk_bf16_f32 v159, v86, v87
	s_waitcnt lgkmcnt(14)
	v_mfma_f32_32x32x16_bf16 v[112:127], v[184:187], v[152:155], v[112:127]
	ds_read_b64_tr_b16 v[84:85], v65 offset:33792
	ds_read_b64_tr_b16 v[86:87], v65 offset:34304
	v_add_f32_e32 v68, v90, v68
	v_add_f32_e32 v68, v91, v68
	v_add_f32_e32 v68, v92, v68
	v_add_f32_e32 v68, v93, v68
	v_cvt_pk_bf16_f32 v148, v88, v89
	v_cvt_pk_bf16_f32 v149, v90, v91
	s_waitcnt lgkmcnt(14)
	v_mfma_f32_32x32x16_bf16 v[128:143], v[180:183], v[144:147], v[128:143]
	ds_read_b64_tr_b16 v[88:89], v65 offset:37888
	ds_read_b64_tr_b16 v[90:91], v65 offset:38400
	v_add_f32_e32 v68, v94, v68
	v_add_f32_e32 v68, v95, v68
	v_add_f32_e32 v68, 0, v68
	v_cvt_pk_bf16_f32 v150, v92, v93
	v_cvt_pk_bf16_f32 v151, v94, v95
	v_mfma_f32_32x32x16_bf16 v[112:127], v[176:179], v[144:147], v[112:127]
	v_lshl_add_u64 v[70:71], v[208:209], 0, s[56:57]
	v_add_f32_e32 v64, v64, v68
	v_lshl_add_u64 v[244:245], v[70:71], 0, s[44:45]
	v_lshl_add_u64 v[68:69], v[66:67], 0, s[56:57]
	v_lshl_add_u64 v[246:247], v[68:69], 0, s[46:47]
	v_lshl_add_u64 v[248:249], v[68:69], 0, s[48:49]
	s_waitcnt lgkmcnt(14)
	v_mfma_f32_32x32x16_bf16 v[48:63], v[172:175], v[72:75], v[48:63]
	v_exp_f32_e32 v128, v128
	v_exp_f32_e32 v129, v129
	ds_read_b64_tr_b16 v[72:73], v65 offset:26624
	ds_read_b64_tr_b16 v[74:75], v65 offset:27136
	s_waitcnt lgkmcnt(14)
	v_mfma_f32_32x32x16_bf16 v[32:47], v[172:175], v[76:79], v[32:47]
	v_exp_f32_e32 v130, v130
	v_exp_f32_e32 v131, v131
	ds_read_b64_tr_b16 v[76:77], v65 offset:30720
	ds_read_b64_tr_b16 v[78:79], v65 offset:31232
	s_add_i32 s15, s27, s20
	s_mov_b32 m0, s15
	s_nop 0
	global_load_lds_dwordx4 v[244:245], off
	s_waitcnt lgkmcnt(14)
	v_mfma_f32_32x32x16_bf16 v[16:31], v[172:175], v[96:99], v[16:31]
	v_exp_f32_e32 v132, v132
	v_exp_f32_e32 v133, v133
	ds_read_b64_tr_b16 v[92:93], v65 offset:34816
	ds_read_b64_tr_b16 v[94:95], v65 offset:35328
	s_waitcnt lgkmcnt(14)
	v_mfma_f32_32x32x16_bf16 v[0:15], v[172:175], v[100:103], v[0:15]
	v_exp_f32_e32 v134, v134
	v_exp_f32_e32 v135, v135
	ds_read_b64_tr_b16 v[96:97], v65 offset:38912
	ds_read_b64_tr_b16 v[98:99], v65 offset:39424
	s_waitcnt lgkmcnt(14)
	v_mfma_f32_32x32x16_bf16 v[48:63], v[164:167], v[104:107], v[48:63]
	v_exp_f32_e32 v136, v136
	v_exp_f32_e32 v137, v137
	ds_read_b64_tr_b16 v[100:101], v65 offset:27648
	ds_read_b64_tr_b16 v[102:103], v65 offset:28160
	s_lshl_b32 s15, s28, 1
	s_add_i32 s15, s15, s21
	s_mov_b32 m0, s15
	s_nop 0
	global_load_lds_dwordx4 v[246:247], off
	s_waitcnt lgkmcnt(14)
	v_mfma_f32_32x32x16_bf16 v[32:47], v[164:167], v[80:83], v[32:47]
	v_exp_f32_e32 v138, v138
	v_exp_f32_e32 v139, v139
	ds_read_b64_tr_b16 v[80:81], v65 offset:31744
	ds_read_b64_tr_b16 v[82:83], v65 offset:32256
	s_waitcnt lgkmcnt(14)
	v_mfma_f32_32x32x16_bf16 v[16:31], v[164:167], v[84:87], v[16:31]
	v_exp_f32_e32 v140, v140
	v_exp_f32_e32 v141, v141
	ds_read_b64_tr_b16 v[84:85], v65 offset:35840
	ds_read_b64_tr_b16 v[86:87], v65 offset:36352
	s_waitcnt lgkmcnt(14)
	v_mfma_f32_32x32x16_bf16 v[0:15], v[164:167], v[88:91], v[0:15]
	v_exp_f32_e32 v142, v142
	v_exp_f32_e32 v143, v143
	ds_read_b64_tr_b16 v[88:89], v65 offset:39936
	ds_read_b64_tr_b16 v[90:91], v65 offset:40448
	s_lshl_b32 s15, s28, 1
	s_add_i32 s15, s15, s21
	s_addk_i32 s15, 0x2000
	s_mov_b32 m0, s15
	s_nop 0
	global_load_lds_dwordx4 v[248:249], off
	s_waitcnt lgkmcnt(14)
; #define WAIT_BAR(N) asm volatile("s_waitcnt vmcnt(" #N ") lgkmcnt(0)\n\ts_barrier":::"memory")
;   #define ROT() do{sl_prev=sl_cur;sl_cur=sl_next;sl_next=(sl_next==(NSLOT-1)*SLOTB)?0:sl_next+SLOTB;}while(0)
; template<int DUMMY> __device__ __forceinline__ void attn_pass2(const bf16*Qh,const bf16*__restrict__ Kh,const bf16*__restrict__ Vh,const int q0,char*shm,f32x16 (&o)[4]){
;     ...
;   int t=1;
;     ...
;   for(;t+5<NT;t+=2){
;     STEP(pB0,pB1,pA0,pA1,t,true,true,true);     WAIT_BAR(3); ROT();
;     STEP(pA0,pA1,pB0,pB1,t+1,true,true,true);   WAIT_BAR(3); ROT();
	v_mfma_f32_32x32x16_bf16 v[48:63], v[156:159], v[72:75], v[48:63]
	v_exp_f32_e32 v112, v112
	v_exp_f32_e32 v113, v113
	s_waitcnt lgkmcnt(12)
	v_mfma_f32_32x32x16_bf16 v[32:47], v[156:159], v[76:79], v[32:47]
	v_exp_f32_e32 v114, v114
	v_exp_f32_e32 v115, v115
	v_add_u32_e32 v65, s37, v241
	ds_read_b128 v[72:75], v65
	ds_read_b128 v[76:79], v65 offset:512
	s_waitcnt lgkmcnt(12)
	v_mfma_f32_32x32x16_bf16 v[16:31], v[156:159], v[92:95], v[16:31]
	v_exp_f32_e32 v116, v116
	v_exp_f32_e32 v117, v117
	ds_read_b128 v[176:179], v65 offset:2048
	ds_read_b128 v[180:183], v65 offset:2560
	s_waitcnt lgkmcnt(12)
	v_mfma_f32_32x32x16_bf16 v[0:15], v[156:159], v[96:99], v[0:15]
	v_exp_f32_e32 v118, v118
	v_exp_f32_e32 v119, v119
	ds_read_b128 v[184:187], v65 offset:4096
	ds_read_b128 v[188:191], v65 offset:4608
	s_waitcnt lgkmcnt(12)
	v_mfma_f32_32x32x16_bf16 v[48:63], v[148:151], v[100:103], v[48:63]
	v_exp_f32_e32 v120, v120
	v_exp_f32_e32 v121, v121
	ds_read_b128 v[192:195], v65 offset:6144
	ds_read_b128 v[196:199], v65 offset:6656
	s_waitcnt lgkmcnt(12)
	v_mfma_f32_32x32x16_bf16 v[32:47], v[148:151], v[80:83], v[32:47]
	v_exp_f32_e32 v122, v122
	v_exp_f32_e32 v123, v123
	s_waitcnt lgkmcnt(10)
	v_mfma_f32_32x32x16_bf16 v[16:31], v[148:151], v[84:87], v[16:31]
	v_exp_f32_e32 v124, v124
	v_exp_f32_e32 v125, v125
	s_waitcnt lgkmcnt(8)
	v_mfma_f32_32x32x16_bf16 v[0:15], v[148:151], v[88:91], v[0:15]
	v_exp_f32_e32 v126, v126
	v_exp_f32_e32 v127, v127
	s_waitcnt vmcnt(3) lgkmcnt(0)
	s_barrier
	s_add_i32 s15, s28, 0x2000
	s_cmpk_lg_i32 s28, 0x4000
	s_cselect_b32 s27, s15, 0
	v_lshl_add_u32 v65, s14, 1, v239
	ds_read_b64_tr_b16 v[200:201], v65 offset:24576
	ds_read_b64_tr_b16 v[202:203], v65 offset:25088
	s_waitcnt lgkmcnt(9)
	v_mfma_f32_32x32x16_bf16 v[96:111], v[72:75], v[168:171], 0
	v_add_f32_e32 v80, v128, v129
	v_add_f32_e32 v80, v130, v80
	v_add_f32_e32 v80, v131, v80
	v_add_f32_e32 v80, v132, v80
	v_add_f32_e32 v80, v133, v80
	v_cvt_pk_bf16_f32 v172, v128, v129
	v_cvt_pk_bf16_f32 v173, v130, v131
	ds_read_b64_tr_b16 v[72:73], v65 offset:28672
	ds_read_b64_tr_b16 v[74:75], v65 offset:29184
	v_add_f32_e32 v80, v134, v80
	v_add_f32_e32 v80, v135, v80
	v_add_f32_e32 v80, v136, v80
	v_add_f32_e32 v128, v137, v80
	s_waitcnt lgkmcnt(10)
	v_mfma_f32_32x32x16_bf16 v[80:95], v[76:79], v[168:171], 0
	v_cvt_pk_bf16_f32 v174, v132, v133
	v_cvt_pk_bf16_f32 v175, v134, v135
	ds_read_b64_tr_b16 v[76:77], v65 offset:32768
	ds_read_b64_tr_b16 v[78:79], v65 offset:33280
	s_waitcnt lgkmcnt(11)
	v_mfma_f32_32x32x16_bf16 v[96:111], v[176:179], v[160:163], v[96:111]
	v_add_f32_e32 v128, v138, v128
	v_add_f32_e32 v128, v139, v128
	v_add_f32_e32 v128, v140, v128
	v_add_f32_e32 v132, v141, v128
	v_cvt_pk_bf16_f32 v164, v136, v137
	v_cvt_pk_bf16_f32 v165, v138, v139
	ds_read_b64_tr_b16 v[128:129], v65 offset:36864
	ds_read_b64_tr_b16 v[130:131], v65 offset:37376
	s_waitcnt lgkmcnt(12)
	v_mfma_f32_32x32x16_bf16 v[80:95], v[180:183], v[160:163], v[80:95]
	v_add_f32_e32 v132, v142, v132
	v_add_f32_e32 v132, v143, v132
	v_add_f32_e32 v132, v112, v132
	v_add_f32_e32 v136, v113, v132
	v_cvt_pk_bf16_f32 v166, v140, v141
	v_cvt_pk_bf16_f32 v167, v142, v143
	ds_read_b64_tr_b16 v[132:133], v65 offset:25600
	ds_read_b64_tr_b16 v[134:135], v65 offset:26112
	s_waitcnt lgkmcnt(13)
	v_mfma_f32_32x32x16_bf16 v[96:111], v[184:187], v[152:155], v[96:111]
	v_add_f32_e32 v136, v114, v136
	v_add_f32_e32 v136, v115, v136
	v_add_f32_e32 v136, v116, v136
	v_add_f32_e32 v136, v117, v136
	v_cvt_pk_bf16_f32 v156, v112, v113
	v_cvt_pk_bf16_f32 v157, v114, v115
	ds_read_b64_tr_b16 v[112:113], v65 offset:29696
	ds_read_b64_tr_b16 v[114:115], v65 offset:30208
	s_waitcnt lgkmcnt(14)
	v_mfma_f32_32x32x16_bf16 v[80:95], v[188:191], v[152:155], v[80:95]
	v_add_f32_e32 v136, v118, v136
	v_add_f32_e32 v136, v119, v136
	v_add_f32_e32 v136, v120, v136
	v_add_f32_e32 v136, v121, v136
	v_cvt_pk_bf16_f32 v158, v116, v117
	v_cvt_pk_bf16_f32 v159, v118, v119
	ds_read_b64_tr_b16 v[116:117], v65 offset:33792
	ds_read_b64_tr_b16 v[118:119], v65 offset:34304
	s_waitcnt lgkmcnt(14)
; #define WAIT_BAR(N) asm volatile("s_waitcnt vmcnt(" #N ") lgkmcnt(0)\n\ts_barrier":::"memory")
;   #define ROT() do{sl_prev=sl_cur;sl_cur=sl_next;sl_next=(sl_next==(NSLOT-1)*SLOTB)?0:sl_next+SLOTB;}while(0)
; template<int DUMMY> __device__ __forceinline__ void attn_pass2(const bf16*Qh,const bf16*__restrict__ Kh,const bf16*__restrict__ Vh,const int q0,char*shm,f32x16 (&o)[4]){
;     ...
;   int t=1;
;     ...
;   for(;t+5<NT;t+=2){
;     STEP(pB0,pB1,pA0,pA1,t,true,true,true);     WAIT_BAR(3); ROT();
;     STEP(pA0,pA1,pB0,pB1,t+1,true,true,true);   WAIT_BAR(3); ROT();
;   }
	v_mfma_f32_32x32x16_bf16 v[96:111], v[192:195], v[144:147], v[96:111]
	v_add_f32_e32 v136, v122, v136
	v_add_f32_e32 v136, v123, v136
	v_add_f32_e32 v136, v124, v136
	v_add_f32_e32 v136, v125, v136
	v_cvt_pk_bf16_f32 v148, v120, v121
	v_cvt_pk_bf16_f32 v149, v122, v123
	ds_read_b64_tr_b16 v[120:121], v65 offset:37888
	ds_read_b64_tr_b16 v[122:123], v65 offset:38400
	v_mfma_f32_32x32x16_bf16 v[80:95], v[196:199], v[144:147], v[80:95]
	v_add_f32_e32 v136, v126, v136
	v_add_f32_e32 v136, v127, v136
	v_add_f32_e32 v136, 0, v136
	v_cvt_pk_bf16_f32 v150, v124, v125
	v_cvt_pk_bf16_f32 v151, v126, v127
	s_mov_b64 s[14:15], 0x1e0000
	v_lshl_add_u64 v[244:245], v[70:71], 0, s[14:15]
	s_mov_b64 s[14:15], 0x10121000
	v_lshl_add_u64 v[246:247], v[68:69], 0, s[14:15]
	s_mov_b64 s[14:15], 0x10121080
	v_lshl_add_u64 v[248:249], v[68:69], 0, s[14:15]
	v_add_f32_e32 v64, v64, v136
	s_add_i32 s35, s35, 2
	s_waitcnt lgkmcnt(14)
	v_mfma_f32_32x32x16_bf16 v[48:63], v[172:175], v[200:203], v[48:63]
	v_exp_f32_e32 v96, v96
	v_exp_f32_e32 v97, v97
	ds_read_b64_tr_b16 v[68:69], v65 offset:26624
	ds_read_b64_tr_b16 v[70:71], v65 offset:27136
	s_waitcnt lgkmcnt(14)
	v_mfma_f32_32x32x16_bf16 v[32:47], v[172:175], v[72:75], v[32:47]
	v_exp_f32_e32 v98, v98
	v_exp_f32_e32 v99, v99
	ds_read_b64_tr_b16 v[72:73], v65 offset:30720
	ds_read_b64_tr_b16 v[74:75], v65 offset:31232
	s_add_i32 s24, s28, s20
	s_mov_b32 m0, s24
	s_nop 0
	global_load_lds_dwordx4 v[244:245], off
	s_waitcnt lgkmcnt(14)
	v_mfma_f32_32x32x16_bf16 v[16:31], v[172:175], v[76:79], v[16:31]
	v_exp_f32_e32 v100, v100
	v_exp_f32_e32 v101, v101
	ds_read_b64_tr_b16 v[76:77], v65 offset:34816
	ds_read_b64_tr_b16 v[78:79], v65 offset:35328
	s_waitcnt lgkmcnt(14)
	v_mfma_f32_32x32x16_bf16 v[0:15], v[172:175], v[128:131], v[0:15]
	v_exp_f32_e32 v102, v102
	v_exp_f32_e32 v103, v103
	ds_read_b64_tr_b16 v[124:125], v65 offset:38912
	ds_read_b64_tr_b16 v[126:127], v65 offset:39424
	s_waitcnt lgkmcnt(14)
	v_mfma_f32_32x32x16_bf16 v[48:63], v[164:167], v[132:135], v[48:63]
	v_exp_f32_e32 v104, v104
	v_exp_f32_e32 v105, v105
	ds_read_b64_tr_b16 v[128:129], v65 offset:27648
	ds_read_b64_tr_b16 v[130:131], v65 offset:28160
	s_lshl_b32 s24, s27, 1
	s_add_i32 s24, s24, s21
	s_mov_b32 m0, s24
	s_nop 0
	global_load_lds_dwordx4 v[246:247], off
	s_waitcnt lgkmcnt(14)
	v_mfma_f32_32x32x16_bf16 v[32:47], v[164:167], v[112:115], v[32:47]
	v_exp_f32_e32 v106, v106
	v_exp_f32_e32 v107, v107
	ds_read_b64_tr_b16 v[112:113], v65 offset:31744
	ds_read_b64_tr_b16 v[114:115], v65 offset:32256
	s_waitcnt lgkmcnt(14)
	v_mfma_f32_32x32x16_bf16 v[16:31], v[164:167], v[116:119], v[16:31]
	v_exp_f32_e32 v108, v108
	v_exp_f32_e32 v109, v109
	ds_read_b64_tr_b16 v[116:117], v65 offset:35840
	ds_read_b64_tr_b16 v[118:119], v65 offset:36352
	s_waitcnt lgkmcnt(14)
	v_mfma_f32_32x32x16_bf16 v[0:15], v[164:167], v[120:123], v[0:15]
	v_exp_f32_e32 v110, v110
	v_exp_f32_e32 v111, v111
	ds_read_b64_tr_b16 v[120:121], v65 offset:39936
	ds_read_b64_tr_b16 v[122:123], v65 offset:40448
	s_lshl_b32 s24, s27, 1
	s_add_i32 s24, s24, s21
	s_addk_i32 s24, 0x2000
	s_mov_b32 m0, s24
	s_nop 0
	global_load_lds_dwordx4 v[248:249], off
	s_waitcnt lgkmcnt(14)
	v_mfma_f32_32x32x16_bf16 v[48:63], v[156:159], v[68:71], v[48:63]
	v_exp_f32_e32 v80, v80
	v_exp_f32_e32 v81, v81
	s_waitcnt lgkmcnt(12)
	v_mfma_f32_32x32x16_bf16 v[32:47], v[156:159], v[72:75], v[32:47]
	v_exp_f32_e32 v82, v82
	v_exp_f32_e32 v83, v83
	v_add_u32_e32 v65, s27, v241
	ds_read_b128 v[204:207], v65
	ds_read_b128 v[200:203], v65 offset:512
	s_waitcnt lgkmcnt(12)
	v_mfma_f32_32x32x16_bf16 v[16:31], v[156:159], v[76:79], v[16:31]
	v_exp_f32_e32 v84, v84
	v_exp_f32_e32 v85, v85
	ds_read_b128 v[196:199], v65 offset:2048
	ds_read_b128 v[192:195], v65 offset:2560
	s_waitcnt lgkmcnt(12)
	v_mfma_f32_32x32x16_bf16 v[0:15], v[156:159], v[124:127], v[0:15]
	v_exp_f32_e32 v86, v86
	v_exp_f32_e32 v87, v87
	ds_read_b128 v[188:191], v65 offset:4096
	ds_read_b128 v[184:187], v65 offset:4608
	s_waitcnt lgkmcnt(12)
	v_mfma_f32_32x32x16_bf16 v[48:63], v[148:151], v[128:131], v[48:63]
	v_exp_f32_e32 v88, v88
	v_exp_f32_e32 v89, v89
	ds_read_b128 v[180:183], v65 offset:6144
	ds_read_b128 v[176:179], v65 offset:6656
	s_waitcnt lgkmcnt(12)
	v_mfma_f32_32x32x16_bf16 v[32:47], v[148:151], v[112:115], v[32:47]
	v_exp_f32_e32 v90, v90
	v_exp_f32_e32 v91, v91
	s_waitcnt lgkmcnt(10)
	v_mfma_f32_32x32x16_bf16 v[16:31], v[148:151], v[116:119], v[16:31]
	v_exp_f32_e32 v92, v92
	v_exp_f32_e32 v93, v93
	s_waitcnt lgkmcnt(8)
	v_mfma_f32_32x32x16_bf16 v[0:15], v[148:151], v[120:123], v[0:15]
	v_exp_f32_e32 v94, v94
	v_exp_f32_e32 v95, v95
	s_add_i32 s14, s27, 0x2000
	s_cmpk_lg_i32 s27, 0x4000
	s_waitcnt vmcnt(3) lgkmcnt(0)
	s_barrier
	s_cselect_b32 s28, s14, 0
	s_add_u32 s56, s56, 0xc0000
	s_addc_u32 s57, s57, 0
	s_cmp_ge_i32 s35, s11
	s_mov_b32 s15, s37
	s_cbranch_scc0 .LBB0_304
	s_ashr_i32 s11, s10, 31
	s_add_i32 s14, s35, 1
	s_cmp_lt_i32 s14, s25
	s_cbranch_scc1 .LBB0_315
